# removed compiler-inserted vmcnt(0) before LDS reads in both DMA GEMM loops (P1, P4c) so the next k-tile DMA overlaps compute
# speedup vs baseline: 1.0139x; 1.0139x over previous
.LBB0_175:
	v_or_b32_e32 v2, 0x10000, v118
	v_lshl_add_u64 v[86:87], s[80:81], 0, v[84:85]
	v_readfirstlane_b32 s0, v2
	v_lshl_add_u64 v[88:89], v[86:87], 0, s[8:9]
	s_mov_b32 m0, s0
	v_or_b32_e32 v2, 0x18000, v118
	global_load_lds_dwordx4 v[88:89], off
	v_lshl_add_u64 v[88:89], s[80:81], 0, v[68:69]
	v_readfirstlane_b32 s0, v2
	v_lshl_add_u64 v[90:91], v[88:89], 0, s[10:11]
	s_mov_b32 m0, s0
	v_or_b32_e32 v2, 0x10000, v119
	global_load_lds_dwordx4 v[90:91], off
	v_lshl_add_u64 v[90:91], s[80:81], 0, v[82:83]
	v_readfirstlane_b32 s0, v2
	v_lshl_add_u64 v[92:93], v[90:91], 0, s[8:9]
	s_mov_b32 m0, s0
	v_or_b32_e32 v2, 0x18000, v119
	global_load_lds_dwordx4 v[92:93], off
	v_lshl_add_u64 v[92:93], s[80:81], 0, v[66:67]
	v_readfirstlane_b32 s0, v2
	v_lshl_add_u64 v[94:95], v[92:93], 0, s[10:11]
	s_mov_b32 m0, s0
	v_or_b32_e32 v2, 0x10000, v120
	global_load_lds_dwordx4 v[94:95], off
	v_lshl_add_u64 v[94:95], s[80:81], 0, v[80:81]
	v_readfirstlane_b32 s0, v2
	v_lshl_add_u64 v[96:97], v[94:95], 0, s[8:9]
	s_mov_b32 m0, s0
	v_or_b32_e32 v2, 0x18000, v120
	global_load_lds_dwordx4 v[96:97], off
	v_lshl_add_u64 v[96:97], s[80:81], 0, v[64:65]
	v_readfirstlane_b32 s0, v2
	v_lshl_add_u64 v[98:99], v[96:97], 0, s[10:11]
	s_mov_b32 m0, s0
	v_or_b32_e32 v2, 0x10000, v121
	global_load_lds_dwordx4 v[98:99], off
	v_lshl_add_u64 v[98:99], s[80:81], 0, v[78:79]
	v_readfirstlane_b32 s0, v2
	v_lshl_add_u64 v[100:101], v[98:99], 0, s[8:9]
	s_mov_b32 m0, s0
	v_or_b32_e32 v2, 0x18000, v121
	global_load_lds_dwordx4 v[100:101], off
	v_lshl_add_u64 v[100:101], s[80:81], 0, v[62:63]
	v_readfirstlane_b32 s0, v2
	v_lshl_add_u64 v[102:103], v[100:101], 0, s[10:11]
	s_mov_b32 m0, s0
	v_or_b32_e32 v2, 0x10000, v122
	global_load_lds_dwordx4 v[102:103], off
	v_lshl_add_u64 v[102:103], s[80:81], 0, v[76:77]
	v_readfirstlane_b32 s0, v2
	v_lshl_add_u64 v[104:105], v[102:103], 0, s[8:9]
	s_mov_b32 m0, s0
	v_or_b32_e32 v2, 0x18000, v122
	global_load_lds_dwordx4 v[104:105], off
	v_lshl_add_u64 v[104:105], s[80:81], 0, v[60:61]
	v_readfirstlane_b32 s0, v2
	v_lshl_add_u64 v[106:107], v[104:105], 0, s[10:11]
	s_mov_b32 m0, s0
	v_or_b32_e32 v2, 0x10000, v123
	global_load_lds_dwordx4 v[106:107], off
	v_lshl_add_u64 v[106:107], s[80:81], 0, v[74:75]
	v_readfirstlane_b32 s0, v2
	v_lshl_add_u64 v[108:109], v[106:107], 0, s[8:9]
	s_mov_b32 m0, s0
	v_add_u32_e32 v2, 0x18000, v123
	global_load_lds_dwordx4 v[108:109], off
	v_lshl_add_u64 v[108:109], s[80:81], 0, v[58:59]
	v_readfirstlane_b32 s0, v2
	v_lshl_add_u64 v[110:111], v[108:109], 0, s[10:11]
	s_mov_b32 m0, s0
	v_or_b32_e32 v2, 0x10000, v124
	global_load_lds_dwordx4 v[110:111], off
	v_lshl_add_u64 v[110:111], s[80:81], 0, v[72:73]
	v_readfirstlane_b32 s0, v2
	v_lshl_add_u64 v[112:113], v[110:111], 0, s[8:9]
	s_mov_b32 m0, s0
	v_add_u32_e32 v2, 0x18000, v124
	global_load_lds_dwordx4 v[112:113], off
	v_lshl_add_u64 v[112:113], s[80:81], 0, v[56:57]
	v_readfirstlane_b32 s0, v2
	v_lshl_add_u64 v[114:115], v[112:113], 0, s[10:11]
	s_mov_b32 m0, s0
	v_or_b32_e32 v2, 0x10000, v125
	global_load_lds_dwordx4 v[114:115], off
	v_lshl_add_u64 v[114:115], s[80:81], 0, v[70:71]
	v_readfirstlane_b32 s0, v2
	v_lshl_add_u64 v[116:117], v[114:115], 0, s[8:9]
	s_mov_b32 m0, s0
	v_add_u32_e32 v2, 0x18000, v125
	global_load_lds_dwordx4 v[116:117], off
	v_lshl_add_u64 v[116:117], s[80:81], 0, v[54:55]
	v_readfirstlane_b32 s0, v2
	v_lshl_add_u64 v[176:177], v[116:117], 0, s[10:11]
	s_mov_b32 m0, s0
	s_nop 0
	global_load_lds_dwordx4 v[176:177], off
	ds_read_b128 v[176:179], v126
	ds_read_b128 v[180:183], v126 offset:8192
	ds_read_b128 v[184:187], v127 offset:32768
	ds_read_b128 v[188:191], v127 offset:40960
	ds_read_b128 v[192:195], v130
	ds_read_b128 v[196:199], v130 offset:8192
	ds_read_b128 v[202:205], v131 offset:32768
	ds_read_b128 v[206:209], v131 offset:40960
	s_waitcnt lgkmcnt(0)
	v_mfma_f32_32x32x16_bf16 a[48:63], v[176:179], v[184:187], a[48:63]
	v_mfma_f32_32x32x16_bf16 a[32:47], v[176:179], v[188:191], a[32:47]
	v_mfma_f32_32x32x16_bf16 a[16:31], v[180:183], v[184:187], a[16:31]
	v_mfma_f32_32x32x16_bf16 a[0:15], v[180:183], v[188:191], a[0:15]
	ds_read_b128 v[176:179], v132 offset:40960
	ds_read_b128 v[180:183], v132 offset:32768
	ds_read_b128 v[184:187], v133 offset:8192
	ds_read_b128 v[188:191], v133
	v_mfma_f32_32x32x16_bf16 a[48:63], v[192:195], v[202:205], a[48:63]
	v_mfma_f32_32x32x16_bf16 a[32:47], v[192:195], v[206:209], a[32:47]
	v_mfma_f32_32x32x16_bf16 a[16:31], v[196:199], v[202:205], a[16:31]
	v_mfma_f32_32x32x16_bf16 a[0:15], v[196:199], v[206:209], a[0:15]
	ds_read_b128 v[192:195], v134
	ds_read_b128 v[196:199], v134 offset:8192
	ds_read_b128 v[202:205], v136 offset:32768
	ds_read_b128 v[206:209], v136 offset:40960
	s_waitcnt lgkmcnt(4)
; __device__ __forceinline__ void gemm_mainloop_dma(f32x16 (&acc)[2][2], const u16* __restrict__ A, int lda, const u16* __restrict__ Bt, int ldb, int K, char* smem) {
;     ...
;   for (int kt = 0; kt < KT; kt += 2) {
;     if (kt + 1 < KT) { GL_DMA(kt + 1, 1) }
;     GL_COMPUTE(0)
;     asm volatile("s_waitcnt vmcnt(0)" ::: "memory");
;     __syncthreads();
;     if (kt + 1 < KT) {
;       if (kt + 2 < KT) { GL_DMA(kt + 2, 0) }
	v_mfma_f32_32x32x16_bf16 a[48:63], v[188:191], v[180:183], a[48:63]
	v_mfma_f32_32x32x16_bf16 a[32:47], v[188:191], v[176:179], a[32:47]
	v_mfma_f32_32x32x16_bf16 a[16:31], v[184:187], v[180:183], a[16:31]
	v_mfma_f32_32x32x16_bf16 a[0:15], v[184:187], v[176:179], a[0:15]
	ds_read_b128 v[176:179], v138 offset:40960
	ds_read_b128 v[180:183], v138 offset:32768
	ds_read_b128 v[184:187], v139 offset:8192
	ds_read_b128 v[188:191], v139
	s_waitcnt lgkmcnt(5)
	v_mfma_f32_32x32x16_bf16 a[48:63], v[192:195], v[202:205], a[48:63]
	s_waitcnt lgkmcnt(4)
	v_mfma_f32_32x32x16_bf16 a[32:47], v[192:195], v[206:209], a[32:47]
	v_mfma_f32_32x32x16_bf16 a[16:31], v[196:199], v[202:205], a[16:31]
	v_mfma_f32_32x32x16_bf16 a[0:15], v[196:199], v[206:209], a[0:15]
	ds_read_b128 v[192:195], v141
	ds_read_b128 v[196:199], v141 offset:8192
	ds_read_b128 v[202:205], v142 offset:32768
	ds_read_b128 v[206:209], v142 offset:40960
	s_waitcnt lgkmcnt(4)
	v_mfma_f32_32x32x16_bf16 a[48:63], v[188:191], v[180:183], a[48:63]
	v_mfma_f32_32x32x16_bf16 a[32:47], v[188:191], v[176:179], a[32:47]
	v_mfma_f32_32x32x16_bf16 a[16:31], v[184:187], v[180:183], a[16:31]
	v_mfma_f32_32x32x16_bf16 a[0:15], v[184:187], v[176:179], a[0:15]
	ds_read_b128 v[176:179], v143 offset:40960
	ds_read_b128 v[180:183], v143 offset:32768
	ds_read_b128 v[184:187], v144 offset:8192
	ds_read_b128 v[188:191], v144
	s_waitcnt lgkmcnt(5)
	v_mfma_f32_32x32x16_bf16 a[48:63], v[192:195], v[202:205], a[48:63]
	s_waitcnt lgkmcnt(4)
	v_mfma_f32_32x32x16_bf16 a[32:47], v[192:195], v[206:209], a[32:47]
	v_mfma_f32_32x32x16_bf16 a[16:31], v[196:199], v[202:205], a[16:31]
	v_mfma_f32_32x32x16_bf16 a[0:15], v[196:199], v[206:209], a[0:15]
	ds_read_b128 v[192:195], v145
	ds_read_b128 v[196:199], v145 offset:8192
	ds_read_b128 v[202:205], v146 offset:32768
	ds_read_b128 v[206:209], v146 offset:40960
	s_waitcnt lgkmcnt(4)
	v_mfma_f32_32x32x16_bf16 a[48:63], v[188:191], v[180:183], a[48:63]
	v_mfma_f32_32x32x16_bf16 a[32:47], v[188:191], v[176:179], a[32:47]
	v_mfma_f32_32x32x16_bf16 a[16:31], v[184:187], v[180:183], a[16:31]
	v_mfma_f32_32x32x16_bf16 a[0:15], v[184:187], v[176:179], a[0:15]
	s_waitcnt lgkmcnt(1)
	v_mfma_f32_32x32x16_bf16 a[48:63], v[192:195], v[202:205], a[48:63]
	s_waitcnt lgkmcnt(0)
	v_mfma_f32_32x32x16_bf16 a[32:47], v[192:195], v[206:209], a[32:47]
	v_mfma_f32_32x32x16_bf16 a[16:31], v[196:199], v[202:205], a[16:31]
	v_mfma_f32_32x32x16_bf16 a[0:15], v[196:199], v[206:209], a[0:15]
	s_waitcnt vmcnt(0)
	s_cmp_gt_u32 s2, 5
	s_cselect_b64 s[0:1], -1, 0
	s_and_b64 vcc, exec, s[0:1]
	s_barrier
	s_cbranch_vccnz .LBB0_174
	v_readfirstlane_b32 s4, v118
	v_lshl_add_u64 v[86:87], v[86:87], 0, s[12:13]
	s_mov_b32 m0, s4
	v_readfirstlane_b32 s4, v241
	global_load_lds_dwordx4 v[86:87], off
	v_lshl_add_u64 v[86:87], v[88:89], 0, s[14:15]
	s_mov_b32 m0, s4
	v_readfirstlane_b32 s4, v119
	global_load_lds_dwordx4 v[86:87], off
	v_lshl_add_u64 v[86:87], v[90:91], 0, s[12:13]
	s_mov_b32 m0, s4
	v_readfirstlane_b32 s4, v242
	global_load_lds_dwordx4 v[86:87], off
	v_lshl_add_u64 v[86:87], v[92:93], 0, s[14:15]
	s_mov_b32 m0, s4
	v_readfirstlane_b32 s4, v120
	global_load_lds_dwordx4 v[86:87], off
	v_lshl_add_u64 v[86:87], v[94:95], 0, s[12:13]
	s_mov_b32 m0, s4
	v_readfirstlane_b32 s4, v243
	global_load_lds_dwordx4 v[86:87], off
	v_lshl_add_u64 v[86:87], v[96:97], 0, s[14:15]
	s_mov_b32 m0, s4
	v_readfirstlane_b32 s4, v121
	global_load_lds_dwordx4 v[86:87], off
	v_lshl_add_u64 v[86:87], v[98:99], 0, s[12:13]
	s_mov_b32 m0, s4
	v_readfirstlane_b32 s4, v244
	global_load_lds_dwordx4 v[86:87], off
	v_lshl_add_u64 v[86:87], v[100:101], 0, s[14:15]
	s_mov_b32 m0, s4
	v_readfirstlane_b32 s4, v122
	global_load_lds_dwordx4 v[86:87], off
	v_lshl_add_u64 v[86:87], v[102:103], 0, s[12:13]
	s_mov_b32 m0, s4
	v_readfirstlane_b32 s4, v245
	global_load_lds_dwordx4 v[86:87], off
	v_lshl_add_u64 v[86:87], v[104:105], 0, s[14:15]
	s_mov_b32 m0, s4
	v_readfirstlane_b32 s4, v123
	global_load_lds_dwordx4 v[86:87], off
	v_lshl_add_u64 v[86:87], v[106:107], 0, s[12:13]
	s_mov_b32 m0, s4
	v_readfirstlane_b32 s4, v246
	global_load_lds_dwordx4 v[86:87], off
	v_lshl_add_u64 v[86:87], v[108:109], 0, s[14:15]
	s_mov_b32 m0, s4
	v_readfirstlane_b32 s4, v124
	global_load_lds_dwordx4 v[86:87], off
	v_lshl_add_u64 v[86:87], v[110:111], 0, s[12:13]
	s_mov_b32 m0, s4
	v_readfirstlane_b32 s4, v247
	global_load_lds_dwordx4 v[86:87], off
	v_lshl_add_u64 v[86:87], v[112:113], 0, s[14:15]
	s_mov_b32 m0, s4
	v_readfirstlane_b32 s4, v125
	global_load_lds_dwordx4 v[86:87], off
	v_lshl_add_u64 v[86:87], v[114:115], 0, s[12:13]
	s_mov_b32 m0, s4
	v_readfirstlane_b32 s4, v248
	global_load_lds_dwordx4 v[86:87], off
	v_lshl_add_u64 v[86:87], v[116:117], 0, s[14:15]
	s_mov_b32 m0, s4
	s_nop 0
	global_load_lds_dwordx4 v[86:87], off
	s_branch .LBB0_174

.LBB0_1418:
	v_or_b32_e32 v6, 0x10000, v116
	v_lshl_add_u64 v[84:85], s[80:81], 0, v[82:83]
	v_readfirstlane_b32 s0, v6
	v_or_b32_e32 v6, 0x18000, v116
	v_lshl_add_u64 v[8:9], v[84:85], 0, s[6:7]
	s_mov_b32 m0, s0
	v_lshl_add_u64 v[86:87], s[80:81], 0, v[66:67]
	v_readfirstlane_b32 s0, v6
	v_or_b32_e32 v6, 0x10000, v117
	global_load_lds_dwordx4 v[8:9], off
	v_lshl_add_u64 v[8:9], v[86:87], 0, s[8:9]
	s_mov_b32 m0, s0
	v_lshl_add_u64 v[88:89], s[80:81], 0, v[80:81]
	v_readfirstlane_b32 s0, v6
	v_or_b32_e32 v6, 0x18000, v117
	global_load_lds_dwordx4 v[8:9], off
	v_lshl_add_u64 v[8:9], v[88:89], 0, s[6:7]
	s_mov_b32 m0, s0
	v_lshl_add_u64 v[90:91], s[80:81], 0, v[64:65]
	v_readfirstlane_b32 s0, v6
	v_or_b32_e32 v6, 0x10000, v118
	global_load_lds_dwordx4 v[8:9], off
	v_lshl_add_u64 v[8:9], v[90:91], 0, s[8:9]
	s_mov_b32 m0, s0
	v_lshl_add_u64 v[92:93], s[80:81], 0, v[78:79]
	v_readfirstlane_b32 s0, v6
	v_or_b32_e32 v6, 0x18000, v118
	global_load_lds_dwordx4 v[8:9], off
	v_lshl_add_u64 v[8:9], v[92:93], 0, s[6:7]
	s_mov_b32 m0, s0
	v_lshl_add_u64 v[94:95], s[80:81], 0, v[62:63]
	v_readfirstlane_b32 s0, v6
	v_or_b32_e32 v6, 0x10000, v119
	global_load_lds_dwordx4 v[8:9], off
	v_lshl_add_u64 v[8:9], v[94:95], 0, s[8:9]
	s_mov_b32 m0, s0
	v_lshl_add_u64 v[96:97], s[80:81], 0, v[76:77]
	v_readfirstlane_b32 s0, v6
	v_or_b32_e32 v6, 0x18000, v119
	global_load_lds_dwordx4 v[8:9], off
	v_lshl_add_u64 v[8:9], v[96:97], 0, s[6:7]
	s_mov_b32 m0, s0
	v_lshl_add_u64 v[98:99], s[80:81], 0, v[60:61]
	v_readfirstlane_b32 s0, v6
	v_or_b32_e32 v6, 0x10000, v120
	global_load_lds_dwordx4 v[8:9], off
	v_lshl_add_u64 v[8:9], v[98:99], 0, s[8:9]
	s_mov_b32 m0, s0
	v_lshl_add_u64 v[100:101], s[80:81], 0, v[74:75]
	v_readfirstlane_b32 s0, v6
	v_or_b32_e32 v6, 0x18000, v120
	global_load_lds_dwordx4 v[8:9], off
	v_lshl_add_u64 v[8:9], v[100:101], 0, s[6:7]
	s_mov_b32 m0, s0
	v_lshl_add_u64 v[102:103], s[80:81], 0, v[58:59]
	v_readfirstlane_b32 s0, v6
	v_or_b32_e32 v6, 0x10000, v121
	global_load_lds_dwordx4 v[8:9], off
	v_lshl_add_u64 v[8:9], v[102:103], 0, s[8:9]
	s_mov_b32 m0, s0
	v_lshl_add_u64 v[104:105], s[80:81], 0, v[72:73]
	v_readfirstlane_b32 s0, v6
	v_add_u32_e32 v6, 0x18000, v121
	global_load_lds_dwordx4 v[8:9], off
	v_lshl_add_u64 v[8:9], v[104:105], 0, s[6:7]
	s_mov_b32 m0, s0
	v_lshl_add_u64 v[106:107], s[80:81], 0, v[56:57]
	v_readfirstlane_b32 s0, v6
	v_or_b32_e32 v6, 0x10000, v122
	global_load_lds_dwordx4 v[8:9], off
	v_lshl_add_u64 v[8:9], v[106:107], 0, s[8:9]
	s_mov_b32 m0, s0
	v_lshl_add_u64 v[108:109], s[80:81], 0, v[70:71]
	v_readfirstlane_b32 s0, v6
	v_add_u32_e32 v6, 0x18000, v122
	global_load_lds_dwordx4 v[8:9], off
	v_lshl_add_u64 v[8:9], v[108:109], 0, s[6:7]
	s_mov_b32 m0, s0
	v_lshl_add_u64 v[110:111], s[80:81], 0, v[2:3]
	v_readfirstlane_b32 s0, v6
	v_or_b32_e32 v6, 0x10000, v123
	global_load_lds_dwordx4 v[8:9], off
	v_lshl_add_u64 v[8:9], v[110:111], 0, s[8:9]
	s_mov_b32 m0, s0
	v_lshl_add_u64 v[112:113], s[80:81], 0, v[68:69]
	v_readfirstlane_b32 s0, v6
	v_add_u32_e32 v6, 0x18000, v123
	global_load_lds_dwordx4 v[8:9], off
	v_lshl_add_u64 v[8:9], v[112:113], 0, s[6:7]
	s_mov_b32 m0, s0
	v_lshl_add_u64 v[114:115], s[80:81], 0, v[0:1]
	v_readfirstlane_b32 s0, v6
	global_load_lds_dwordx4 v[8:9], off
	v_lshl_add_u64 v[8:9], v[114:115], 0, s[8:9]
	s_mov_b32 m0, s0
	s_nop 0
	global_load_lds_dwordx4 v[8:9], off
	ds_read_b128 v[182:185], v124
	ds_read_b128 v[186:189], v124 offset:8192
	ds_read_b128 v[190:193], v125 offset:32768
	ds_read_b128 v[240:243], v125 offset:40960
	ds_read_b128 v[244:247], v128
	ds_read_b128 v[248:251], v128 offset:8192
	ds_read_b128 v[176:179], v129 offset:32768
	ds_read_b128 v[8:11], v129 offset:40960
	s_waitcnt lgkmcnt(0)
	v_mfma_f32_32x32x16_bf16 a[48:63], v[182:185], v[190:193], a[48:63]
	v_mfma_f32_32x32x16_bf16 a[32:47], v[182:185], v[240:243], a[32:47]
	v_mfma_f32_32x32x16_bf16 a[16:31], v[186:189], v[190:193], a[16:31]
	v_mfma_f32_32x32x16_bf16 a[0:15], v[186:189], v[240:243], a[0:15]
	ds_read_b128 v[182:185], v130 offset:40960
	ds_read_b128 v[186:189], v130 offset:32768
	ds_read_b128 v[190:193], v131 offset:8192
	ds_read_b128 v[240:243], v131
	v_mfma_f32_32x32x16_bf16 a[48:63], v[244:247], v[176:179], a[48:63]
	v_mfma_f32_32x32x16_bf16 a[32:47], v[244:247], v[8:11], a[32:47]
	v_mfma_f32_32x32x16_bf16 a[16:31], v[248:251], v[176:179], a[16:31]
	v_mfma_f32_32x32x16_bf16 a[0:15], v[248:251], v[8:11], a[0:15]
	ds_read_b128 v[8:11], v132
	ds_read_b128 v[176:179], v132 offset:8192
	ds_read_b128 v[244:247], v133 offset:32768
	ds_read_b128 v[248:251], v133 offset:40960
	s_waitcnt lgkmcnt(4)
; __device__ __forceinline__ void gemm_mainloop_dma(f32x16 (&acc)[2][2], const u16* __restrict__ A, int lda, const u16* __restrict__ Bt, int ldb, int K, char* smem) {
;     ...
;   for (int kt = 0; kt < KT; kt += 2) {
;     if (kt + 1 < KT) { GL_DMA(kt + 1, 1) }
;     GL_COMPUTE(0)
;     asm volatile("s_waitcnt vmcnt(0)" ::: "memory");
;     __syncthreads();
;     if (kt + 1 < KT) {
;       if (kt + 2 < KT) { GL_DMA(kt + 2, 0) }
	v_mfma_f32_32x32x16_bf16 a[48:63], v[240:243], v[186:189], a[48:63]
	v_mfma_f32_32x32x16_bf16 a[32:47], v[240:243], v[182:185], a[32:47]
	v_mfma_f32_32x32x16_bf16 a[16:31], v[190:193], v[186:189], a[16:31]
	v_mfma_f32_32x32x16_bf16 a[0:15], v[190:193], v[182:185], a[0:15]
	ds_read_b128 v[182:185], v134 offset:40960
	ds_read_b128 v[186:189], v134 offset:32768
	ds_read_b128 v[190:193], v136 offset:8192
	ds_read_b128 v[240:243], v136
	s_waitcnt lgkmcnt(5)
	v_mfma_f32_32x32x16_bf16 a[48:63], v[8:11], v[244:247], a[48:63]
	s_waitcnt lgkmcnt(4)
	v_mfma_f32_32x32x16_bf16 a[32:47], v[8:11], v[248:251], a[32:47]
	v_mfma_f32_32x32x16_bf16 a[16:31], v[176:179], v[244:247], a[16:31]
	v_mfma_f32_32x32x16_bf16 a[0:15], v[176:179], v[248:251], a[0:15]
	ds_read_b128 v[8:11], v138
	ds_read_b128 v[176:179], v138 offset:8192
	ds_read_b128 v[244:247], v139 offset:32768
	ds_read_b128 v[248:251], v139 offset:40960
	s_waitcnt lgkmcnt(4)
	v_mfma_f32_32x32x16_bf16 a[48:63], v[240:243], v[186:189], a[48:63]
	v_mfma_f32_32x32x16_bf16 a[32:47], v[240:243], v[182:185], a[32:47]
	v_mfma_f32_32x32x16_bf16 a[16:31], v[190:193], v[186:189], a[16:31]
	v_mfma_f32_32x32x16_bf16 a[0:15], v[190:193], v[182:185], a[0:15]
	ds_read_b128 v[182:185], v140 offset:40960
	ds_read_b128 v[186:189], v140 offset:32768
	ds_read_b128 v[190:193], v141 offset:8192
	ds_read_b128 v[240:243], v141
	s_waitcnt lgkmcnt(5)
	v_mfma_f32_32x32x16_bf16 a[48:63], v[8:11], v[244:247], a[48:63]
	s_waitcnt lgkmcnt(4)
	v_mfma_f32_32x32x16_bf16 a[32:47], v[8:11], v[248:251], a[32:47]
	v_mfma_f32_32x32x16_bf16 a[16:31], v[176:179], v[244:247], a[16:31]
	v_mfma_f32_32x32x16_bf16 a[0:15], v[176:179], v[248:251], a[0:15]
	ds_read_b128 v[8:11], v142
	ds_read_b128 v[176:179], v142 offset:8192
	ds_read_b128 v[244:247], v143 offset:32768
	ds_read_b128 v[248:251], v143 offset:40960
	s_waitcnt lgkmcnt(4)
	v_mfma_f32_32x32x16_bf16 a[48:63], v[240:243], v[186:189], a[48:63]
	v_mfma_f32_32x32x16_bf16 a[32:47], v[240:243], v[182:185], a[32:47]
	v_mfma_f32_32x32x16_bf16 a[16:31], v[190:193], v[186:189], a[16:31]
	v_mfma_f32_32x32x16_bf16 a[0:15], v[190:193], v[182:185], a[0:15]
	s_waitcnt lgkmcnt(1)
	v_mfma_f32_32x32x16_bf16 a[48:63], v[8:11], v[244:247], a[48:63]
	s_waitcnt lgkmcnt(0)
	v_mfma_f32_32x32x16_bf16 a[32:47], v[8:11], v[248:251], a[32:47]
	v_mfma_f32_32x32x16_bf16 a[16:31], v[176:179], v[244:247], a[16:31]
	v_mfma_f32_32x32x16_bf16 a[0:15], v[176:179], v[248:251], a[0:15]
	s_waitcnt vmcnt(0)
	s_cmp_gt_u32 s21, 5
	s_cselect_b64 s[0:1], -1, 0
	s_and_b64 vcc, exec, s[0:1]
	s_barrier
	s_cbranch_vccnz .LBB0_1417
	v_readfirstlane_b32 s33, v116
	v_lshl_add_u64 v[8:9], v[84:85], 0, s[10:11]
	s_mov_b32 m0, s33
	v_readfirstlane_b32 s33, v196
	global_load_lds_dwordx4 v[8:9], off
	v_lshl_add_u64 v[8:9], v[86:87], 0, s[12:13]
	s_mov_b32 m0, s33
	v_readfirstlane_b32 s33, v117
	global_load_lds_dwordx4 v[8:9], off
	v_lshl_add_u64 v[8:9], v[88:89], 0, s[10:11]
	s_mov_b32 m0, s33
	v_readfirstlane_b32 s33, v197
	global_load_lds_dwordx4 v[8:9], off
	v_lshl_add_u64 v[8:9], v[90:91], 0, s[12:13]
	s_mov_b32 m0, s33
	v_readfirstlane_b32 s33, v118
	global_load_lds_dwordx4 v[8:9], off
	v_lshl_add_u64 v[8:9], v[92:93], 0, s[10:11]
	s_mov_b32 m0, s33
	v_readfirstlane_b32 s33, v198
	global_load_lds_dwordx4 v[8:9], off
	v_lshl_add_u64 v[8:9], v[94:95], 0, s[12:13]
	s_mov_b32 m0, s33
	v_readfirstlane_b32 s33, v119
	global_load_lds_dwordx4 v[8:9], off
	v_lshl_add_u64 v[8:9], v[96:97], 0, s[10:11]
	s_mov_b32 m0, s33
	v_readfirstlane_b32 s33, v199
	global_load_lds_dwordx4 v[8:9], off
	v_lshl_add_u64 v[8:9], v[98:99], 0, s[12:13]
	s_mov_b32 m0, s33
	v_readfirstlane_b32 s33, v120
	global_load_lds_dwordx4 v[8:9], off
	v_lshl_add_u64 v[8:9], v[100:101], 0, s[10:11]
	s_mov_b32 m0, s33
	v_readfirstlane_b32 s33, v200
	global_load_lds_dwordx4 v[8:9], off
	v_lshl_add_u64 v[8:9], v[102:103], 0, s[12:13]
	s_mov_b32 m0, s33
	v_readfirstlane_b32 s33, v121
	global_load_lds_dwordx4 v[8:9], off
	v_lshl_add_u64 v[8:9], v[104:105], 0, s[10:11]
	s_mov_b32 m0, s33
	v_readfirstlane_b32 s33, v201
	global_load_lds_dwordx4 v[8:9], off
	v_lshl_add_u64 v[8:9], v[106:107], 0, s[12:13]
	s_mov_b32 m0, s33
	v_readfirstlane_b32 s33, v122
	global_load_lds_dwordx4 v[8:9], off
	v_lshl_add_u64 v[8:9], v[108:109], 0, s[10:11]
	s_mov_b32 m0, s33
	v_readfirstlane_b32 s33, v202
	global_load_lds_dwordx4 v[8:9], off
	v_lshl_add_u64 v[8:9], v[110:111], 0, s[12:13]
	s_mov_b32 m0, s33
	v_readfirstlane_b32 s33, v123
	global_load_lds_dwordx4 v[8:9], off
	v_lshl_add_u64 v[8:9], v[112:113], 0, s[10:11]
	s_mov_b32 m0, s33
	v_readfirstlane_b32 s33, v203
	global_load_lds_dwordx4 v[8:9], off
	v_lshl_add_u64 v[8:9], v[114:115], 0, s[12:13]
	s_mov_b32 m0, s33
	s_nop 0
	global_load_lds_dwordx4 v[8:9], off
	s_branch .LBB0_1417
